# P9 MB stores sc1 nt (on top of P8 deferred stores + sc1 nt)
# baseline (speedup 1.0000x reference)
.LBB0_957:
	v_mul_f32_e32 v157, v125, v125
	v_mul_f32_e32 v160, v127, v127
	v_fmac_f32_e32 v157, v124, v124
	v_fmac_f32_e32 v160, v126, v126
	v_add_f32_e32 v157, v157, v160
	v_mul_f32_e32 v160, v121, v121
	v_fmac_f32_e32 v160, v120, v120
	v_cvt_pk_bf16_f32 v124, v124, v125
	v_cvt_pk_bf16_f32 v125, v126, v127
	v_cvt_pk_bf16_f32 v126, v120, v121
	v_mul_f32_e32 v120, v117, v117
	v_mul_f32_e32 v121, v119, v119
	v_fmac_f32_e32 v120, v116, v116
	v_fmac_f32_e32 v121, v118, v118
	v_add_f32_e32 v120, v120, v121
	v_mul_f32_e32 v121, v113, v113
	v_and_b32_e32 v155, 64, v154
	v_fmac_f32_e32 v121, v112, v112
	v_xor_b32_e32 v147, 16, v154
	v_add_u32_e32 v155, 64, v155
	v_add_f32_e32 v157, v157, v160
	v_mul_f32_e32 v160, v123, v123
	v_add_f32_e32 v120, v120, v121
	v_mul_f32_e32 v121, v115, v115
	v_cmp_lt_i32_e32 vcc, v147, v155
	v_fmac_f32_e32 v160, v122, v122
	v_fmac_f32_e32 v121, v114, v114
	v_cndmask_b32_e32 v147, v154, v147, vcc
	v_add_f32_e32 v157, v160, v157
	v_add_f32_e32 v120, v121, v120
	v_lshlrev_b32_e32 v156, 2, v147
	v_xor_b32_e32 v147, 32, v154
	v_cvt_pk_bf16_f32 v127, v122, v123
	v_add_f32_e32 v122, v157, v120
	v_cmp_lt_i32_e32 vcc, v147, v155
	ds_bpermute_b32 v123, v156, v122
	v_lshl_add_u32 v146, s30, 8, v148
	v_cndmask_b32_e32 v147, v154, v147, vcc
	v_lshlrev_b32_e32 v155, 2, v147
	v_ashrrev_i32_e32 v147, 31, v146
	v_lshl_or_b32 v144, s14, 8, v150
	v_lshlrev_b64 v[158:159], 11, v[146:147]
	v_ashrrev_i32_e32 v145, 31, v144
	v_lshl_add_u64 v[120:121], s[66:67], 0, v[158:159]
	v_lshl_add_u64 v[158:159], v[144:145], 1, v[120:121]
	v_cvt_pk_bf16_f32 v120, v116, v117
	s_waitcnt lgkmcnt(0)
	v_add_f32_e32 v116, v122, v123
	ds_bpermute_b32 v117, v155, v116
	s_lshl_b32 s30, s14, 2
	s_ashr_i32 s31, s30, 31
	v_cvt_pk_bf16_f32 v121, v118, v119
	v_cvt_pk_bf16_f32 v122, v112, v113
	v_cvt_pk_bf16_f32 v123, v114, v115
	global_store_dwordx4 v[158:159], v[124:127], off sc1 nt
	global_store_dwordx4 v[158:159], v[120:123], off offset:256 sc1 nt
	s_and_saveexec_b64 s[34:35], s[4:5]
	s_cbranch_execz .LBB0_959
	v_lshlrev_b64 v[112:113], 6, v[146:147]
	v_lshl_add_u64 v[112:113], s[0:1], 0, v[112:113]
	v_lshl_add_u64 v[112:113], s[30:31], 2, v[112:113]
	s_lshl_b32 s14, s45, 2
	s_waitcnt lgkmcnt(0)
	v_add_f32_e32 v114, v116, v117
	v_lshl_add_u64 v[112:113], v[112:113], 0, s[14:15]
	global_store_dword v[112:113], v114, off
.LBB0_959:
	s_or_b64 exec, exec, s[34:35]
	v_mul_f32_e32 v116, v109, v109
	s_waitcnt lgkmcnt(0)
	v_mul_f32_e32 v117, v111, v111
	v_fmac_f32_e32 v116, v108, v108
	v_fmac_f32_e32 v117, v110, v110
	v_add_f32_e32 v116, v116, v117
	v_mul_f32_e32 v117, v105, v105
	v_fmac_f32_e32 v117, v104, v104
	v_cvt_pk_bf16_f32 v108, v108, v109
	v_cvt_pk_bf16_f32 v109, v110, v111
	v_cvt_pk_bf16_f32 v110, v104, v105
	v_mul_f32_e32 v104, v101, v101
	v_mul_f32_e32 v105, v103, v103
	v_fmac_f32_e32 v104, v100, v100
	v_fmac_f32_e32 v105, v102, v102
	v_add_f32_e32 v104, v104, v105
	v_mul_f32_e32 v105, v97, v97
	v_fmac_f32_e32 v105, v96, v96
	v_add_f32_e32 v116, v116, v117
	v_mul_f32_e32 v117, v107, v107
	v_add_f32_e32 v104, v104, v105
	v_mul_f32_e32 v105, v99, v99
	v_fmac_f32_e32 v117, v106, v106
	v_fmac_f32_e32 v105, v98, v98
	v_add_f32_e32 v116, v117, v116
	v_add_f32_e32 v104, v105, v104
	v_cvt_pk_bf16_f32 v111, v106, v107
	v_add_f32_e32 v106, v116, v104
	ds_bpermute_b32 v107, v156, v106
	v_or_b32_e32 v112, 16, v146
	v_ashrrev_i32_e32 v113, 31, v112
	v_lshlrev_b64 v[114:115], 11, v[112:113]
	v_lshl_add_u64 v[104:105], s[66:67], 0, v[114:115]
	v_lshl_add_u64 v[114:115], v[144:145], 1, v[104:105]
	v_cvt_pk_bf16_f32 v104, v100, v101
	s_waitcnt lgkmcnt(0)
	v_add_f32_e32 v100, v106, v107
	ds_bpermute_b32 v101, v155, v100
	v_cvt_pk_bf16_f32 v105, v102, v103
	v_cvt_pk_bf16_f32 v106, v96, v97
	v_cvt_pk_bf16_f32 v107, v98, v99
	global_store_dwordx4 v[114:115], v[108:111], off sc1 nt
	global_store_dwordx4 v[114:115], v[104:107], off offset:256 sc1 nt
	s_and_saveexec_b64 s[34:35], s[4:5]
	s_cbranch_execz .LBB0_961
	v_lshlrev_b64 v[96:97], 6, v[112:113]
	v_lshl_add_u64 v[96:97], s[0:1], 0, v[96:97]
	v_lshl_add_u64 v[96:97], s[30:31], 2, v[96:97]
	s_lshl_b32 s14, s45, 2
	s_waitcnt lgkmcnt(0)
	v_add_f32_e32 v98, v100, v101
	v_lshl_add_u64 v[96:97], v[96:97], 0, s[14:15]
	global_store_dword v[96:97], v98, off
.LBB0_961:
	s_or_b64 exec, exec, s[34:35]
	v_mul_f32_e32 v100, v93, v93
	s_waitcnt lgkmcnt(0)
	v_mul_f32_e32 v101, v95, v95
	v_fmac_f32_e32 v100, v92, v92
	v_fmac_f32_e32 v101, v94, v94
	v_add_f32_e32 v100, v100, v101
	v_mul_f32_e32 v101, v89, v89
	v_fmac_f32_e32 v101, v88, v88
	v_cvt_pk_bf16_f32 v92, v92, v93
	v_cvt_pk_bf16_f32 v93, v94, v95
	v_cvt_pk_bf16_f32 v94, v88, v89
	v_mul_f32_e32 v88, v85, v85
	v_mul_f32_e32 v89, v87, v87
	v_fmac_f32_e32 v88, v84, v84
	v_fmac_f32_e32 v89, v86, v86
	v_add_f32_e32 v88, v88, v89
	v_mul_f32_e32 v89, v81, v81
	v_fmac_f32_e32 v89, v80, v80
	v_add_f32_e32 v100, v100, v101
	v_mul_f32_e32 v101, v91, v91
	v_add_f32_e32 v88, v88, v89
	v_mul_f32_e32 v89, v83, v83
	v_fmac_f32_e32 v101, v90, v90
	v_fmac_f32_e32 v89, v82, v82
	v_add_f32_e32 v100, v101, v100
	v_add_f32_e32 v88, v89, v88
	v_cvt_pk_bf16_f32 v95, v90, v91
	v_add_f32_e32 v90, v100, v88
	ds_bpermute_b32 v91, v156, v90
	v_or_b32_e32 v96, 32, v146
	v_ashrrev_i32_e32 v97, 31, v96
	v_lshlrev_b64 v[98:99], 11, v[96:97]
	v_lshl_add_u64 v[88:89], s[66:67], 0, v[98:99]
	v_lshl_add_u64 v[98:99], v[144:145], 1, v[88:89]
	v_cvt_pk_bf16_f32 v88, v84, v85
	s_waitcnt lgkmcnt(0)
	v_add_f32_e32 v84, v90, v91
	ds_bpermute_b32 v85, v155, v84
	v_cvt_pk_bf16_f32 v89, v86, v87
	v_cvt_pk_bf16_f32 v90, v80, v81
	v_cvt_pk_bf16_f32 v91, v82, v83
	global_store_dwordx4 v[98:99], v[92:95], off sc1 nt
	global_store_dwordx4 v[98:99], v[88:91], off offset:256 sc1 nt
	s_and_saveexec_b64 s[34:35], s[4:5]
	s_cbranch_execz .LBB0_963
	v_lshlrev_b64 v[80:81], 6, v[96:97]
	v_lshl_add_u64 v[80:81], s[0:1], 0, v[80:81]
	v_lshl_add_u64 v[80:81], s[30:31], 2, v[80:81]
	s_lshl_b32 s14, s45, 2
	s_waitcnt lgkmcnt(0)
	v_add_f32_e32 v82, v84, v85
	v_lshl_add_u64 v[80:81], v[80:81], 0, s[14:15]
	global_store_dword v[80:81], v82, off
.LBB0_963:
	s_or_b64 exec, exec, s[34:35]
	v_mul_f32_e32 v84, v77, v77
	s_waitcnt lgkmcnt(0)
	v_mul_f32_e32 v85, v79, v79
	v_fmac_f32_e32 v84, v76, v76
	v_fmac_f32_e32 v85, v78, v78
	v_add_f32_e32 v84, v84, v85
	v_mul_f32_e32 v85, v73, v73
	v_fmac_f32_e32 v85, v72, v72
	v_cvt_pk_bf16_f32 v76, v76, v77
	v_cvt_pk_bf16_f32 v77, v78, v79
	v_cvt_pk_bf16_f32 v78, v72, v73
	v_mul_f32_e32 v72, v69, v69
	v_mul_f32_e32 v73, v71, v71
	v_fmac_f32_e32 v72, v68, v68
	v_fmac_f32_e32 v73, v70, v70
	v_add_f32_e32 v72, v72, v73
	v_mul_f32_e32 v73, v65, v65
	v_fmac_f32_e32 v73, v64, v64
	v_add_f32_e32 v84, v84, v85
	v_mul_f32_e32 v85, v75, v75
	v_add_f32_e32 v72, v72, v73
	v_mul_f32_e32 v73, v67, v67
	v_fmac_f32_e32 v85, v74, v74
	v_fmac_f32_e32 v73, v66, v66
	v_add_f32_e32 v84, v85, v84
	v_add_f32_e32 v72, v73, v72
	v_cvt_pk_bf16_f32 v79, v74, v75
	v_add_f32_e32 v74, v84, v72
	ds_bpermute_b32 v75, v156, v74
	v_or_b32_e32 v80, 48, v146
	v_ashrrev_i32_e32 v81, 31, v80
	v_lshlrev_b64 v[82:83], 11, v[80:81]
	v_lshl_add_u64 v[72:73], s[66:67], 0, v[82:83]
	v_lshl_add_u64 v[82:83], v[144:145], 1, v[72:73]
	v_cvt_pk_bf16_f32 v72, v68, v69
	s_waitcnt lgkmcnt(0)
	v_add_f32_e32 v68, v74, v75
	ds_bpermute_b32 v69, v155, v68
	v_cvt_pk_bf16_f32 v73, v70, v71
	v_cvt_pk_bf16_f32 v74, v64, v65
	v_cvt_pk_bf16_f32 v75, v66, v67
	global_store_dwordx4 v[82:83], v[76:79], off sc1 nt
	global_store_dwordx4 v[82:83], v[72:75], off offset:256 sc1 nt
	s_and_saveexec_b64 s[34:35], s[4:5]
	s_cbranch_execz .LBB0_965
	v_lshlrev_b64 v[64:65], 6, v[80:81]
	v_lshl_add_u64 v[64:65], s[0:1], 0, v[64:65]
	v_lshl_add_u64 v[64:65], s[30:31], 2, v[64:65]
	s_lshl_b32 s14, s45, 2
	s_waitcnt lgkmcnt(0)
	v_add_f32_e32 v66, v68, v69
	v_lshl_add_u64 v[64:65], v[64:65], 0, s[14:15]
	global_store_dword v[64:65], v66, off
.LBB0_965:
	s_or_b64 exec, exec, s[34:35]
	v_mul_f32_e32 v68, v61, v61
	s_waitcnt lgkmcnt(0)
	v_mul_f32_e32 v69, v63, v63
	v_fmac_f32_e32 v68, v60, v60
	v_fmac_f32_e32 v69, v62, v62
	v_add_f32_e32 v68, v68, v69
	v_mul_f32_e32 v69, v57, v57
	v_fmac_f32_e32 v69, v56, v56
	v_cvt_pk_bf16_f32 v60, v60, v61
	v_cvt_pk_bf16_f32 v61, v62, v63
	v_cvt_pk_bf16_f32 v62, v56, v57
	v_mul_f32_e32 v56, v53, v53
	v_mul_f32_e32 v57, v55, v55
	v_fmac_f32_e32 v56, v52, v52
	v_fmac_f32_e32 v57, v54, v54
	v_add_f32_e32 v56, v56, v57
	v_mul_f32_e32 v57, v49, v49
	v_fmac_f32_e32 v57, v48, v48
	v_add_f32_e32 v68, v68, v69
	v_mul_f32_e32 v69, v59, v59
	v_add_f32_e32 v56, v56, v57
	v_mul_f32_e32 v57, v51, v51
	v_fmac_f32_e32 v69, v58, v58
	v_fmac_f32_e32 v57, v50, v50
	v_add_f32_e32 v68, v69, v68
	v_add_f32_e32 v56, v57, v56
	v_cvt_pk_bf16_f32 v63, v58, v59
	v_add_f32_e32 v58, v68, v56
	ds_bpermute_b32 v59, v156, v58
	v_add_u32_e32 v64, 0x80, v146
	v_ashrrev_i32_e32 v65, 31, v64
	v_lshlrev_b64 v[66:67], 11, v[64:65]
	v_lshl_add_u64 v[56:57], s[66:67], 0, v[66:67]
	v_lshl_add_u64 v[66:67], v[144:145], 1, v[56:57]
	v_cvt_pk_bf16_f32 v56, v52, v53
	s_waitcnt lgkmcnt(0)
	v_add_f32_e32 v52, v58, v59
	ds_bpermute_b32 v53, v155, v52
	v_cvt_pk_bf16_f32 v57, v54, v55
	v_cvt_pk_bf16_f32 v58, v48, v49
	v_cvt_pk_bf16_f32 v59, v50, v51
	global_store_dwordx4 v[66:67], v[60:63], off sc1 nt
	global_store_dwordx4 v[66:67], v[56:59], off offset:256 sc1 nt
	s_and_saveexec_b64 s[34:35], s[4:5]
	s_cbranch_execz .LBB0_967
	v_lshlrev_b64 v[48:49], 6, v[64:65]
	v_lshl_add_u64 v[48:49], s[0:1], 0, v[48:49]
	v_lshl_add_u64 v[48:49], s[30:31], 2, v[48:49]
	s_lshl_b32 s14, s45, 2
	s_waitcnt lgkmcnt(0)
	v_add_f32_e32 v50, v52, v53
	v_lshl_add_u64 v[48:49], v[48:49], 0, s[14:15]
	global_store_dword v[48:49], v50, off
.LBB0_967:
	s_or_b64 exec, exec, s[34:35]
	v_mul_f32_e32 v52, v45, v45
	s_waitcnt lgkmcnt(0)
	v_mul_f32_e32 v53, v47, v47
	v_fmac_f32_e32 v52, v44, v44
	v_fmac_f32_e32 v53, v46, v46
	v_add_f32_e32 v52, v52, v53
	v_mul_f32_e32 v53, v41, v41
	v_fmac_f32_e32 v53, v40, v40
	v_cvt_pk_bf16_f32 v44, v44, v45
	v_cvt_pk_bf16_f32 v45, v46, v47
	v_cvt_pk_bf16_f32 v46, v40, v41
	v_mul_f32_e32 v40, v37, v37
	v_mul_f32_e32 v41, v39, v39
	v_fmac_f32_e32 v40, v36, v36
	v_fmac_f32_e32 v41, v38, v38
	v_add_f32_e32 v40, v40, v41
	v_mul_f32_e32 v41, v33, v33
	v_fmac_f32_e32 v41, v32, v32
	v_add_f32_e32 v52, v52, v53
	v_mul_f32_e32 v53, v43, v43
	v_add_f32_e32 v40, v40, v41
	v_mul_f32_e32 v41, v35, v35
	v_fmac_f32_e32 v53, v42, v42
	v_fmac_f32_e32 v41, v34, v34
	v_add_f32_e32 v52, v53, v52
	v_add_f32_e32 v40, v41, v40
	v_cvt_pk_bf16_f32 v47, v42, v43
	v_add_f32_e32 v42, v52, v40
	ds_bpermute_b32 v43, v156, v42
	v_add_u32_e32 v48, 0x90, v146
	v_ashrrev_i32_e32 v49, 31, v48
	v_lshlrev_b64 v[50:51], 11, v[48:49]
	v_lshl_add_u64 v[40:41], s[66:67], 0, v[50:51]
	v_lshl_add_u64 v[50:51], v[144:145], 1, v[40:41]
	v_cvt_pk_bf16_f32 v40, v36, v37
	s_waitcnt lgkmcnt(0)
	v_add_f32_e32 v36, v42, v43
	ds_bpermute_b32 v37, v155, v36
	v_cvt_pk_bf16_f32 v41, v38, v39
	v_cvt_pk_bf16_f32 v42, v32, v33
	v_cvt_pk_bf16_f32 v43, v34, v35
	global_store_dwordx4 v[50:51], v[44:47], off sc1 nt
	global_store_dwordx4 v[50:51], v[40:43], off offset:256 sc1 nt
	s_and_saveexec_b64 s[34:35], s[4:5]
	s_cbranch_execz .LBB0_969
	v_lshlrev_b64 v[32:33], 6, v[48:49]
	v_lshl_add_u64 v[32:33], s[0:1], 0, v[32:33]
	v_lshl_add_u64 v[32:33], s[30:31], 2, v[32:33]
	s_lshl_b32 s14, s45, 2
	s_waitcnt lgkmcnt(0)
	v_add_f32_e32 v34, v36, v37
	v_lshl_add_u64 v[32:33], v[32:33], 0, s[14:15]
	global_store_dword v[32:33], v34, off
.LBB0_969:
	s_or_b64 exec, exec, s[34:35]
	v_mul_f32_e32 v36, v29, v29
	s_waitcnt lgkmcnt(0)
	v_mul_f32_e32 v37, v31, v31
	v_fmac_f32_e32 v36, v28, v28
	v_fmac_f32_e32 v37, v30, v30
	v_add_f32_e32 v36, v36, v37
	v_mul_f32_e32 v37, v25, v25
	v_fmac_f32_e32 v37, v24, v24
	v_cvt_pk_bf16_f32 v28, v28, v29
	v_cvt_pk_bf16_f32 v29, v30, v31
	v_cvt_pk_bf16_f32 v30, v24, v25
	v_mul_f32_e32 v24, v21, v21
	v_mul_f32_e32 v25, v23, v23
	v_fmac_f32_e32 v24, v20, v20
	v_fmac_f32_e32 v25, v22, v22
	v_add_f32_e32 v24, v24, v25
	v_mul_f32_e32 v25, v17, v17
	v_fmac_f32_e32 v25, v16, v16
	v_add_f32_e32 v36, v36, v37
	v_mul_f32_e32 v37, v27, v27
	v_add_f32_e32 v24, v24, v25
	v_mul_f32_e32 v25, v19, v19
	v_fmac_f32_e32 v37, v26, v26
	v_fmac_f32_e32 v25, v18, v18
	v_add_f32_e32 v36, v37, v36
	v_add_f32_e32 v24, v25, v24
	v_cvt_pk_bf16_f32 v31, v26, v27
	v_add_f32_e32 v26, v36, v24
	ds_bpermute_b32 v27, v156, v26
	v_add_u32_e32 v32, 0xa0, v146
	v_ashrrev_i32_e32 v33, 31, v32
	v_lshlrev_b64 v[34:35], 11, v[32:33]
	v_lshl_add_u64 v[24:25], s[66:67], 0, v[34:35]
	v_lshl_add_u64 v[34:35], v[144:145], 1, v[24:25]
	v_cvt_pk_bf16_f32 v24, v20, v21
	s_waitcnt lgkmcnt(0)
	v_add_f32_e32 v20, v26, v27
	ds_bpermute_b32 v21, v155, v20
	v_cvt_pk_bf16_f32 v25, v22, v23
	v_cvt_pk_bf16_f32 v26, v16, v17
	v_cvt_pk_bf16_f32 v27, v18, v19
	global_store_dwordx4 v[34:35], v[28:31], off sc1 nt
	global_store_dwordx4 v[34:35], v[24:27], off offset:256 sc1 nt
	s_and_saveexec_b64 s[34:35], s[4:5]
	s_cbranch_execz .LBB0_971
	v_lshlrev_b64 v[16:17], 6, v[32:33]
	v_lshl_add_u64 v[16:17], s[0:1], 0, v[16:17]
	v_lshl_add_u64 v[16:17], s[30:31], 2, v[16:17]
	s_lshl_b32 s14, s45, 2
	s_waitcnt lgkmcnt(0)
	v_add_f32_e32 v18, v20, v21
	v_lshl_add_u64 v[16:17], v[16:17], 0, s[14:15]
	global_store_dword v[16:17], v18, off
.LBB0_971:
	s_or_b64 exec, exec, s[34:35]
	v_mul_f32_e32 v20, v13, v13
	s_waitcnt lgkmcnt(0)
	v_mul_f32_e32 v21, v15, v15
	v_fmac_f32_e32 v20, v12, v12
	v_fmac_f32_e32 v21, v14, v14
	v_add_f32_e32 v20, v20, v21
	v_mul_f32_e32 v21, v9, v9
	v_fmac_f32_e32 v21, v8, v8
	v_cvt_pk_bf16_f32 v12, v12, v13
	v_cvt_pk_bf16_f32 v13, v14, v15
	v_cvt_pk_bf16_f32 v14, v8, v9
	v_mul_f32_e32 v8, v5, v5
	v_mul_f32_e32 v9, v7, v7
	v_fmac_f32_e32 v8, v4, v4
	v_fmac_f32_e32 v9, v6, v6
	v_add_f32_e32 v8, v8, v9
	v_mul_f32_e32 v9, v1, v1
	v_fmac_f32_e32 v9, v0, v0
	v_add_f32_e32 v20, v20, v21
	v_mul_f32_e32 v21, v11, v11
	v_add_f32_e32 v8, v8, v9
	v_mul_f32_e32 v9, v3, v3
	v_fmac_f32_e32 v21, v10, v10
	v_fmac_f32_e32 v9, v2, v2
	v_add_f32_e32 v20, v21, v20
	v_add_f32_e32 v8, v9, v8
	v_cvt_pk_bf16_f32 v15, v10, v11
	v_add_f32_e32 v10, v20, v8
	ds_bpermute_b32 v11, v156, v10
	v_add_u32_e32 v16, 0xb0, v146
	v_ashrrev_i32_e32 v17, 31, v16
	v_lshlrev_b64 v[18:19], 11, v[16:17]
	v_lshl_add_u64 v[8:9], s[66:67], 0, v[18:19]
	v_lshl_add_u64 v[18:19], v[144:145], 1, v[8:9]
	v_cvt_pk_bf16_f32 v8, v4, v5
	s_waitcnt lgkmcnt(0)
	v_add_f32_e32 v4, v10, v11
	ds_bpermute_b32 v5, v155, v4
	v_cvt_pk_bf16_f32 v9, v6, v7
	v_cvt_pk_bf16_f32 v10, v0, v1
	v_cvt_pk_bf16_f32 v11, v2, v3
	global_store_dwordx4 v[18:19], v[12:15], off sc1 nt
	global_store_dwordx4 v[18:19], v[8:11], off offset:256 sc1 nt
	s_and_saveexec_b64 s[34:35], s[4:5]
	s_cbranch_execz .LBB0_973
	v_lshlrev_b64 v[0:1], 6, v[16:17]
	v_lshl_add_u64 v[0:1], s[0:1], 0, v[0:1]
	v_lshl_add_u64 v[0:1], s[30:31], 2, v[0:1]
	s_lshl_b32 s14, s45, 2
	s_waitcnt lgkmcnt(0)
	v_add_f32_e32 v2, v4, v5
	v_lshl_add_u64 v[0:1], v[0:1], 0, s[14:15]
	global_store_dword v[0:1], v2, off
